# v070 plus write-through stores in the row-half SwiGLU epilogue (same policy as the full-tile epilogue)
# speedup vs baseline: 1.0088x; 1.0088x over previous
; DI unsigned pk2(float lo, float hi) { f32x2 v = {lo, hi}; return __builtin_bit_cast(unsigned, __builtin_convertvector(v, bf2_t)); }
;     DI void operator()(const f32x4 (&acc)[2][2][4][2], const Unit& u, int wr, int wc, int fr, int fq) const {
;         const int row0 = u.pm * BM + rowoff * HALF + wr * 64 + fr, col0 = u.pn * HALF + wc * 32 + 8 * fq;
; #pragma unroll
;         for (int m = 0; m < 4; ++m) {
;             bf16_t* rowp = H + (size_t)(row0 + m * 16) * ldh + col0;
;             const f32x4 g0 = acc[0][0][m][0], g1 = acc[0][0][m][1], u0 = acc[0][1][m][0], u1 = acc[0][1][m][1];
;             const f32x2 ha = swiglu_pk((f32x2){g0[0], g0[1]}, (f32x2){u0[0], u0[1]}), hb = swiglu_pk((f32x2){g0[2], g0[3]}, (f32x2){u0[2], u0[3]});
;             const f32x2 hc = swiglu_pk((f32x2){g1[0], g1[1]}, (f32x2){u1[0], u1[1]}), hd = swiglu_pk((f32x2){g1[2], g1[3]}, (f32x2){u1[2], u1[3]});
;             u32x4 w; w.x = pk2(ha.x, ha.y); w.y = pk2(hb.x, hb.y); w.z = pk2(hc.x, hc.y); w.w = pk2(hd.x, hd.y);
;             *(u32x4*)rowp = w;
;         }
.LBB0_254:
	s_and_b32 s4, 0xffff, s11
	v_lshl_or_b32 v64, s4, 7, v75
	v_or_b32_e32 v68, s25, v64
	v_lshlrev_b32_e32 v96, 1, v68
	v_pk_mul_f32 v[68:69], v[60:61], s[30:31] op_sel_hi:[1,0]
	s_and_b32 s3, s2, 0xffffff80
	v_exp_f32_e32 v68, v68
	v_exp_f32_e32 v69, v69
	s_lshl_b32 s5, s10, 8
	s_add_i32 s5, s5, s3
	v_add_u32_e32 v70, s5, v74
	v_pk_add_f32 v[68:69], v[68:69], 1.0 op_sel_hi:[1,0]
	v_mov_b64_e32 v[64:65], s[80:81]
	v_rcp_f32_e32 v68, v68
	v_rcp_f32_e32 v69, v69
	v_mad_i64_i32 v[66:67], s[4:5], v70, s15, v[64:65]
	v_lshl_add_u64 v[66:67], v[66:67], 0, v[96:97]
	v_pk_mul_f32 v[60:61], v[60:61], v[68:69]
	s_mov_b32 s83, s44
	v_pk_mul_f32 v[56:57], v[60:61], v[56:57]
	v_pk_mul_f32 v[60:61], v[62:63], s[30:31] op_sel_hi:[1,0]
	s_nop 0
	v_exp_f32_e32 v60, v60
	v_exp_f32_e32 v61, v61
	s_nop 0
	v_pk_add_f32 v[60:61], v[60:61], 1.0 op_sel_hi:[1,0]
	s_nop 0
	v_rcp_f32_e32 v60, v60
	v_rcp_f32_e32 v61, v61
	s_nop 0
	v_pk_mul_f32 v[60:61], v[62:63], v[60:61]
	s_nop 0
	v_pk_mul_f32 v[58:59], v[60:61], v[58:59]
	v_pk_mul_f32 v[60:61], v[52:53], s[30:31] op_sel_hi:[1,0]
	s_nop 0
	v_exp_f32_e32 v60, v60
	v_exp_f32_e32 v61, v61
	s_nop 0
	v_pk_add_f32 v[60:61], v[60:61], 1.0 op_sel_hi:[1,0]
	s_nop 0
	v_rcp_f32_e32 v60, v60
	v_rcp_f32_e32 v61, v61
	s_nop 0
	v_pk_mul_f32 v[52:53], v[52:53], v[60:61]
	s_nop 0
	v_pk_mul_f32 v[52:53], v[52:53], v[48:49]
	v_pk_mul_f32 v[48:49], v[54:55], s[30:31] op_sel_hi:[1,0]
	s_nop 0
	v_exp_f32_e32 v48, v48
	v_exp_f32_e32 v49, v49
	s_nop 0
	v_pk_add_f32 v[48:49], v[48:49], 1.0 op_sel_hi:[1,0]
	s_nop 0
	v_rcp_f32_e32 v48, v48
	v_rcp_f32_e32 v49, v49
	s_nop 0
	v_pk_mul_f32 v[48:49], v[54:55], v[48:49]
	s_nop 0
	v_pk_mul_f32 v[54:55], v[48:49], v[50:51]
	v_cvt_pk_bf16_f32 v48, v56, v57
	v_cvt_pk_bf16_f32 v49, v58, v59
	v_cvt_pk_bf16_f32 v50, v52, v53
	v_cvt_pk_bf16_f32 v51, v54, v55
	global_store_dwordx4 v[66:67], v[48:51], off sc1
	s_nop 1
	v_pk_mul_f32 v[50:51], v[44:45], s[30:31] op_sel_hi:[1,0]
	v_or_b32_e32 v48, 16, v70
	v_exp_f32_e32 v50, v50
	v_exp_f32_e32 v51, v51
	v_mad_i64_i32 v[48:49], s[4:5], v48, s15, v[64:65]
	v_lshl_add_u64 v[48:49], v[48:49], 0, v[96:97]
	v_pk_add_f32 v[50:51], v[50:51], 1.0 op_sel_hi:[1,0]
	s_nop 0
	v_rcp_f32_e32 v50, v50
	v_rcp_f32_e32 v51, v51
	s_nop 0
	v_pk_mul_f32 v[44:45], v[44:45], v[50:51]
	s_nop 0
	v_pk_mul_f32 v[40:41], v[44:45], v[40:41]
	v_pk_mul_f32 v[44:45], v[46:47], s[30:31] op_sel_hi:[1,0]
	s_nop 0
	v_exp_f32_e32 v44, v44
	v_exp_f32_e32 v45, v45
	s_nop 0
	v_pk_add_f32 v[44:45], v[44:45], 1.0 op_sel_hi:[1,0]
	s_nop 0
	v_rcp_f32_e32 v44, v44
	v_rcp_f32_e32 v45, v45
	s_nop 0
	v_pk_mul_f32 v[44:45], v[46:47], v[44:45]
	s_nop 0
	v_pk_mul_f32 v[42:43], v[44:45], v[42:43]
	v_pk_mul_f32 v[44:45], v[36:37], s[30:31] op_sel_hi:[1,0]
	s_nop 0
	v_exp_f32_e32 v44, v44
	v_exp_f32_e32 v45, v45
	s_nop 0
	v_pk_add_f32 v[44:45], v[44:45], 1.0 op_sel_hi:[1,0]
	s_nop 0
	v_rcp_f32_e32 v44, v44
	v_rcp_f32_e32 v45, v45
	s_nop 0
	v_pk_mul_f32 v[36:37], v[36:37], v[44:45]
	s_nop 0
	v_pk_mul_f32 v[36:37], v[36:37], v[32:33]
	v_pk_mul_f32 v[32:33], v[38:39], s[30:31] op_sel_hi:[1,0]
	s_nop 0
	v_exp_f32_e32 v32, v32
	v_exp_f32_e32 v33, v33
	s_nop 0
	v_pk_add_f32 v[32:33], v[32:33], 1.0 op_sel_hi:[1,0]
	s_nop 0
	v_rcp_f32_e32 v32, v32
	v_rcp_f32_e32 v33, v33
	s_nop 0
	v_pk_mul_f32 v[32:33], v[38:39], v[32:33]
	s_nop 0
	v_pk_mul_f32 v[38:39], v[32:33], v[34:35]
	v_cvt_pk_bf16_f32 v32, v40, v41
	v_cvt_pk_bf16_f32 v33, v42, v43
	v_cvt_pk_bf16_f32 v34, v36, v37
	v_cvt_pk_bf16_f32 v35, v38, v39
	global_store_dwordx4 v[48:49], v[32:35], off sc1
	s_nop 1
	v_pk_mul_f32 v[34:35], v[28:29], s[30:31] op_sel_hi:[1,0]
	v_or_b32_e32 v32, 32, v70
	v_exp_f32_e32 v34, v34
	v_exp_f32_e32 v35, v35
	v_mad_i64_i32 v[32:33], s[4:5], v32, s15, v[64:65]
	v_lshl_add_u64 v[32:33], v[32:33], 0, v[96:97]
	v_pk_add_f32 v[34:35], v[34:35], 1.0 op_sel_hi:[1,0]
	s_nop 0
	v_rcp_f32_e32 v34, v34
	v_rcp_f32_e32 v35, v35
	s_nop 0
	v_pk_mul_f32 v[28:29], v[28:29], v[34:35]
	s_nop 0
	v_pk_mul_f32 v[24:25], v[28:29], v[24:25]
	v_pk_mul_f32 v[28:29], v[30:31], s[30:31] op_sel_hi:[1,0]
	s_nop 0
	v_exp_f32_e32 v28, v28
	v_exp_f32_e32 v29, v29
	s_nop 0
	v_pk_add_f32 v[28:29], v[28:29], 1.0 op_sel_hi:[1,0]
	s_nop 0
	v_rcp_f32_e32 v28, v28
	v_rcp_f32_e32 v29, v29
	s_nop 0
	v_pk_mul_f32 v[28:29], v[30:31], v[28:29]
	s_nop 0
	v_pk_mul_f32 v[26:27], v[28:29], v[26:27]
	v_pk_mul_f32 v[28:29], v[20:21], s[30:31] op_sel_hi:[1,0]
	s_nop 0
	v_exp_f32_e32 v28, v28
	v_exp_f32_e32 v29, v29
	s_nop 0
	v_pk_add_f32 v[28:29], v[28:29], 1.0 op_sel_hi:[1,0]
	s_nop 0
	v_rcp_f32_e32 v28, v28
	v_rcp_f32_e32 v29, v29
	s_nop 0
	v_pk_mul_f32 v[20:21], v[20:21], v[28:29]
	s_nop 0
	v_pk_mul_f32 v[20:21], v[20:21], v[16:17]
	v_pk_mul_f32 v[16:17], v[22:23], s[30:31] op_sel_hi:[1,0]
	s_nop 0
	v_exp_f32_e32 v16, v16
	v_exp_f32_e32 v17, v17
	s_nop 0
	v_pk_add_f32 v[16:17], v[16:17], 1.0 op_sel_hi:[1,0]
	s_nop 0
	v_rcp_f32_e32 v16, v16
	v_rcp_f32_e32 v17, v17
	s_nop 0
	v_pk_mul_f32 v[16:17], v[22:23], v[16:17]
	s_nop 0
	v_pk_mul_f32 v[22:23], v[16:17], v[18:19]
	v_cvt_pk_bf16_f32 v16, v24, v25
	v_cvt_pk_bf16_f32 v17, v26, v27
	v_cvt_pk_bf16_f32 v18, v20, v21
	v_cvt_pk_bf16_f32 v19, v22, v23
	global_store_dwordx4 v[32:33], v[16:19], off sc1
	s_nop 1
	v_pk_mul_f32 v[18:19], v[12:13], s[30:31] op_sel_hi:[1,0]
	v_or_b32_e32 v16, 48, v70
	v_exp_f32_e32 v18, v18
	v_exp_f32_e32 v19, v19
	v_mad_i64_i32 v[16:17], s[4:5], v16, s15, v[64:65]
	v_lshl_add_u64 v[16:17], v[16:17], 0, v[96:97]
	v_pk_add_f32 v[18:19], v[18:19], 1.0 op_sel_hi:[1,0]
	s_nop 0
	v_rcp_f32_e32 v18, v18
	v_rcp_f32_e32 v19, v19
	s_nop 0
	v_pk_mul_f32 v[12:13], v[12:13], v[18:19]
	s_nop 0
	v_pk_mul_f32 v[8:9], v[12:13], v[8:9]
	v_pk_mul_f32 v[12:13], v[14:15], s[30:31] op_sel_hi:[1,0]
	s_nop 0
	v_exp_f32_e32 v12, v12
	v_exp_f32_e32 v13, v13
	s_nop 0
	v_pk_add_f32 v[12:13], v[12:13], 1.0 op_sel_hi:[1,0]
	s_nop 0
	v_rcp_f32_e32 v12, v12
	v_rcp_f32_e32 v13, v13
	s_nop 0
	v_pk_mul_f32 v[12:13], v[14:15], v[12:13]
	s_nop 0
	v_pk_mul_f32 v[10:11], v[12:13], v[10:11]
	v_pk_mul_f32 v[12:13], v[4:5], s[30:31] op_sel_hi:[1,0]
	s_nop 0
	v_exp_f32_e32 v12, v12
	v_exp_f32_e32 v13, v13
	s_nop 0
	v_pk_add_f32 v[12:13], v[12:13], 1.0 op_sel_hi:[1,0]
	s_nop 0
	v_rcp_f32_e32 v12, v12
	v_rcp_f32_e32 v13, v13
	s_nop 0
	v_pk_mul_f32 v[4:5], v[4:5], v[12:13]
	s_nop 0
	v_pk_mul_f32 v[4:5], v[4:5], v[0:1]
	v_pk_mul_f32 v[0:1], v[6:7], s[30:31] op_sel_hi:[1,0]
	s_nop 0
	v_exp_f32_e32 v0, v0
	v_exp_f32_e32 v1, v1
	s_nop 0
	v_pk_add_f32 v[0:1], v[0:1], 1.0 op_sel_hi:[1,0]
	s_nop 0
	v_rcp_f32_e32 v0, v0
	v_rcp_f32_e32 v1, v1
	s_nop 0
	v_pk_mul_f32 v[0:1], v[6:7], v[0:1]
	s_nop 0
	v_pk_mul_f32 v[6:7], v[0:1], v[2:3]
	v_cvt_pk_bf16_f32 v0, v8, v9
	v_cvt_pk_bf16_f32 v1, v10, v11
	v_cvt_pk_bf16_f32 v2, v4, v5
	v_cvt_pk_bf16_f32 v3, v6, v7
	global_store_dwordx4 v[16:17], v[0:3], off sc1
	s_waitcnt vmcnt(0)
	s_barrier
